# MLA loop: P used in MFMA output order (no permlane32 swaps, V fragment rows follow), V DMA pieces issued last and left in flight over the step barrier (vmcnt(2))
# baseline (speedup 1.0000x reference)
.LBB0_42:
	v_add_u32_e32 v166, 0x8000, v166
	v_add_u32_e32 v167, 0x8000, v168
	v_add_u32_e32 v168, 0x8000, v170
	v_add_u32_e32 v169, 0x8000, v172
	v_add_u32_e32 v170, 0x8000, v174
	v_add_u32_e32 v171, 0x8000, v176
	v_add_u32_e32 v172, 0x8000, v178
	v_add_u32_e32 v173, 0x8000, v180
	v_mov_b32_e32 v174, v183
	v_mov_b32_e32 v175, v193
	v_mov_b32_e32 v176, v195
	v_mov_b32_e32 v177, v197
	v_mov_b32_e32 v178, v140
	v_mov_b32_e32 v179, v142
	v_add_u32_e32 v180, 0x100, v138
	v_add_u32_e32 v181, 0x180, v138
	v_mov_b32_e32 v182, v136
	s_add_u32 s98, s74, 0x13480000
	s_addc_u32 s99, s75, 0
	s_add_u32 s100, s74, 0xae04000
	s_addc_u32 s101, s75, 0
	v_mov_b32_e32 v144, v158
	v_mov_b32_e32 v145, v159
	v_mov_b32_e32 v146, v156
	v_mov_b32_e32 v147, v157
	v_mov_b32_e32 v148, v154
	v_mov_b32_e32 v149, v155
	v_mov_b32_e32 v150, v152
	v_mov_b32_e32 v151, v153
	v_mov_b32_e32 v152, v134
	v_mov_b32_e32 v153, v135
	v_mov_b32_e32 v154, v132
	v_mov_b32_e32 v155, v133
	v_mov_b32_e32 v156, v130
	v_mov_b32_e32 v157, v131
	v_mov_b32_e32 v158, v128
	v_mov_b32_e32 v159, v129
	v_mbcnt_lo_u32_b32 v192, -1, 0
	v_mbcnt_hi_u32_b32 v192, -1, v192
	v_and_b32_e32 v192, 32, v192
	v_mad_u32_u24 v192, v192, 56, v161
	v_mov_b32_e32 v242, v198
	v_sub_f32_e32 v198, 0, v222
	v_sub_f32_e32 v199, 0, v222
	v_sub_f32_e32 v200, 0, v222
	v_sub_f32_e32 v201, 0, v222
	v_sub_f32_e32 v202, 0, v222
	v_sub_f32_e32 v203, 0, v222
	v_sub_f32_e32 v204, 0, v222
	v_sub_f32_e32 v205, 0, v222
	v_sub_f32_e32 v206, 0, v222
	v_sub_f32_e32 v207, 0, v222
	v_sub_f32_e32 v208, 0, v222
	v_sub_f32_e32 v209, 0, v222
	v_sub_f32_e32 v210, 0, v222
	v_sub_f32_e32 v211, 0, v222
	v_sub_f32_e32 v212, 0, v222
	v_sub_f32_e32 v213, 0, v222
	v_mov_b32_e32 v128, v236
	v_mov_b32_e32 v129, v238
	v_mov_b32_e32 v130, v234
	v_mov_b32_e32 v131, v237
	v_mov_b32_e32 v132, v233
	v_mov_b32_e32 v133, v235
	v_mov_b32_e32 v134, v231
	v_mov_b32_e32 v135, v232
	v_mov_b32_e32 v136, v228
	v_mov_b32_e32 v137, v230
	v_mov_b32_e32 v138, v227
	v_mov_b32_e32 v139, v229
	v_mov_b32_e32 v140, v224
	v_mov_b32_e32 v141, v226
	v_mov_b32_e32 v142, v223
	v_mov_b32_e32 v143, v225
	ds_read_b128 v[246:249], v164
	ds_read_b128 v[250:253], v164 offset:1024
	ds_read_b128 v[186:189], v164 offset:2048
	ds_read_b128 v[238:241], v164 offset:3072
	s_waitcnt lgkmcnt(0)
.Lmla_loop:
	ds_read_b128 v[214:217], v166 offset:32768
	ds_read_b128 v[218:221], v166 offset:40960
	ds_read_b128 v[222:225], v167 offset:32768
	ds_read_b128 v[226:229], v167 offset:40960
	ds_read_b128 v[230:233], v168 offset:32768
	ds_read_b128 v[234:237], v168 offset:40960
	v_lshl_add_u32 v183, s52, 14, v192
	s_mov_b32 m0, s45
	s_lshl_b32 s8, s49, 14
	global_load_lds_dwordx4 v178, s[98:99]
	v_exp_f32_e32 v144, v144
	v_add_f32_e32 v243, v128, v129
	v_add_f32_e32 v244, v130, v131
	v_exp_f32_e32 v145, v145
	s_waitcnt lgkmcnt(4)
	v_mfma_f32_32x32x16_bf16 v[64:79], v[214:217], v[124:127], v[198:213]
	s_mov_b32 m0, s77
	s_add_i32 s12, s8, s44
	global_load_lds_dwordx4 v179, s[98:99]
	v_cvt_pk_bf16_f32 v128, v128, v129
	v_add_f32_e32 v243, v132, v243
	v_exp_f32_e32 v146, v146
	v_mfma_f32_32x32x16_bf16 v[80:95], v[218:221], v[124:127], v[198:213]
	ds_read_b128 v[214:217], v169 offset:32768
	ds_read_b128 v[218:221], v169 offset:40960
	v_cvt_pk_bf16_f32 v129, v130, v131
	v_add_f32_e32 v244, v133, v244
	v_exp_f32_e32 v147, v147
	s_waitcnt lgkmcnt(4)
	v_mfma_f32_32x32x16_bf16 v[64:79], v[222:225], v[120:123], v[64:79]
	s_mov_b32 m0, s9
	s_nop 0
	global_load_lds_dwordx4 v182, s[100:101]
	s_add_u32 s100, s100, 0x2000
	s_addc_u32 s101, s101, 0
	v_add_f32_e32 v243, v134, v243
	v_cvt_pk_bf16_f32 v130, v132, v133
	v_exp_f32_e32 v148, v148
	v_mfma_f32_32x32x16_bf16 v[80:95], v[226:229], v[120:123], v[80:95]
	ds_read_b128 v[222:225], v170 offset:32768
	ds_read_b128 v[226:229], v170 offset:40960
	v_add_f32_e32 v244, v135, v244
	v_exp_f32_e32 v149, v149
	v_add_f32_e32 v243, v136, v243
	s_waitcnt lgkmcnt(4)
	v_mfma_f32_32x32x16_bf16 v[64:79], v[230:233], v[116:119], v[64:79]
	s_mov_b32 m0, s12
	s_add_i32 s12, s8, s47
	global_load_lds_dwordx4 v180, s[98:99]
	v_cvt_pk_bf16_f32 v131, v134, v135
	v_exp_f32_e32 v150, v150
	v_add_f32_e32 v244, v137, v244
	v_mfma_f32_32x32x16_bf16 v[80:95], v[234:237], v[116:119], v[80:95]
	ds_read_b128 v[230:233], v171 offset:32768
	ds_read_b128 v[234:237], v171 offset:40960
	v_exp_f32_e32 v151, v151
	v_add_f32_e32 v243, v138, v243
	v_cvt_pk_bf16_f32 v132, v136, v137
	s_waitcnt lgkmcnt(4)
	v_mfma_f32_32x32x16_bf16 v[64:79], v[214:217], v[112:115], v[64:79]
	s_mov_b32 m0, s12
	s_nop 0
	global_load_lds_dwordx4 v181, s[98:99]
	s_add_u32 s98, s98, 0x40000
	s_addc_u32 s99, s99, 0
	v_exp_f32_e32 v152, v152
	v_add_f32_e32 v244, v139, v244
	v_exp_f32_e32 v153, v153
	v_mfma_f32_32x32x16_bf16 v[80:95], v[218:221], v[112:115], v[80:95]
	ds_read_b128 v[214:217], v172 offset:32768
	ds_read_b128 v[218:221], v172 offset:40960
	v_add_f32_e32 v243, v140, v243
	v_cvt_pk_bf16_f32 v133, v138, v139
	v_add_f32_e32 v244, v141, v244
	v_exp_f32_e32 v154, v154
	s_waitcnt lgkmcnt(4)
	v_mfma_f32_32x32x16_bf16 v[64:79], v[222:225], v[108:111], v[64:79]
	v_add_f32_e32 v243, v142, v243
	v_exp_f32_e32 v155, v155
	v_cvt_pk_bf16_f32 v134, v140, v141
	v_mfma_f32_32x32x16_bf16 v[80:95], v[226:229], v[108:111], v[80:95]
	ds_read_b128 v[222:225], v173 offset:32768
	ds_read_b128 v[226:229], v173 offset:40960
	v_add_f32_e32 v244, v143, v244
	v_exp_f32_e32 v156, v156
	v_add_f32_e32 v243, v144, v243
	s_waitcnt lgkmcnt(4)
	v_mfma_f32_32x32x16_bf16 v[64:79], v[230:233], v[104:107], v[64:79]
	v_cvt_pk_bf16_f32 v135, v142, v143
	v_exp_f32_e32 v157, v157
	v_add_f32_e32 v244, v145, v244
	v_mfma_f32_32x32x16_bf16 v[80:95], v[234:237], v[104:107], v[80:95]
	ds_read_b128 v[230:233], v174 offset:8192
	ds_read_b128 v[234:237], v174 offset:12288
	v_exp_f32_e32 v158, v158
	v_add_f32_e32 v243, v146, v243
	v_cvt_pk_bf16_f32 v144, v144, v145
	s_waitcnt lgkmcnt(4)
	v_mfma_f32_32x32x16_bf16 v[64:79], v[214:217], v[100:103], v[64:79]
	v_exp_f32_e32 v159, v159
	v_add_f32_e32 v244, v147, v244
	v_add_f32_e32 v243, v148, v243
	v_mfma_f32_32x32x16_bf16 v[80:95], v[218:221], v[100:103], v[80:95]
	ds_read_b128 v[214:217], v175 offset:8192
	ds_read_b128 v[218:221], v175 offset:12288
	v_cvt_pk_bf16_f32 v145, v146, v147
	v_add_f32_e32 v244, v149, v244
	v_add_f32_e32 v243, v150, v243
	v_cvt_pk_bf16_f32 v146, v148, v149
	s_waitcnt lgkmcnt(4)
	v_mfma_f32_32x32x16_bf16 v[64:79], v[222:225], v[96:99], v[64:79]
	v_add_f32_e32 v244, v151, v244
	v_add_f32_e32 v243, v152, v243
	v_cvt_pk_bf16_f32 v147, v150, v151
	v_add_f32_e32 v244, v153, v244
	v_mfma_f32_32x32x16_bf16 v[80:95], v[226:229], v[96:99], v[80:95]
	ds_read_b128 v[222:225], v176 offset:8192
	ds_read_b128 v[226:229], v176 offset:12288
	v_add_f32_e32 v243, v154, v243
	v_cvt_pk_bf16_f32 v148, v152, v153
	v_add_f32_e32 v244, v155, v244
	v_add_f32_e32 v243, v156, v243
	s_waitcnt lgkmcnt(4)
	v_mfma_f32_32x32x16_bf16 v[64:79], v[230:233], v[246:249], v[64:79]
	v_cvt_pk_bf16_f32 v149, v154, v155
	v_add_f32_e32 v244, v157, v244
	v_add_f32_e32 v243, v158, v243
	v_cvt_pk_bf16_f32 v150, v156, v157
	v_mfma_f32_32x32x16_bf16 v[80:95], v[234:237], v[246:249], v[80:95]
	ds_read_b128 v[230:233], v177 offset:8192
	ds_read_b128 v[234:237], v177 offset:12288
	v_add_f32_e32 v244, v159, v244
	v_cvt_pk_bf16_f32 v151, v158, v159
	v_add_f32_e32 v243, v243, v244
	v_mov_b32_e32 v244, v243
	s_waitcnt lgkmcnt(4)
	v_mfma_f32_32x32x16_bf16 v[64:79], v[214:217], v[250:253], v[64:79]
	v_permlane32_swap_b32_e32 v243, v244
	v_add_f32_e32 v243, v243, v244
	v_fma_f32 v163, v163, v242, v243
	v_mfma_f32_32x32x16_bf16 v[80:95], v[218:221], v[250:253], v[80:95]
	ds_read_b64_tr_b16 v[214:215], v183
	ds_read_b64_tr_b16 v[216:217], v183 offset:256
	ds_read_b64_tr_b16 v[218:219], v183 offset:4096
	ds_read_b64_tr_b16 v[220:221], v183 offset:4352
	s_waitcnt lgkmcnt(6)
	v_mfma_f32_32x32x16_bf16 v[64:79], v[222:225], v[186:189], v[64:79]
	v_mfma_f32_32x32x16_bf16 v[80:95], v[226:229], v[186:189], v[80:95]
	ds_read_b64_tr_b16 v[222:223], v183 offset:8192
	ds_read_b64_tr_b16 v[224:225], v183 offset:8448
	ds_read_b64_tr_b16 v[226:227], v183 offset:12288
	ds_read_b64_tr_b16 v[228:229], v183 offset:12544
	s_waitcnt lgkmcnt(8)
	v_mfma_f32_32x32x16_bf16 v[64:79], v[230:233], v[238:241], v[64:79]
	v_mfma_f32_32x32x16_bf16 v[80:95], v[234:237], v[238:241], v[80:95]
	s_waitcnt lgkmcnt(6)
	v_mfma_f32_32x32x16_bf16 v[0:15], v[128:131], v[214:217], v[0:15]
	ds_read_b64_tr_b16 v[136:137], v183 offset:512
	ds_read_b64_tr_b16 v[138:139], v183 offset:768
	s_waitcnt lgkmcnt(6)
	v_mfma_f32_32x32x16_bf16 v[0:15], v[132:135], v[218:221], v[0:15]
	ds_read_b64_tr_b16 v[140:141], v183 offset:4608
	ds_read_b64_tr_b16 v[142:143], v183 offset:4864
	s_waitcnt lgkmcnt(6)
	v_mfma_f32_32x32x16_bf16 v[0:15], v[144:147], v[222:225], v[0:15]
	ds_read_b64_tr_b16 v[152:153], v183 offset:8704
	ds_read_b64_tr_b16 v[154:155], v183 offset:8960
	v_max3_f32 v196, v64, v65, v66
	v_max3_f32 v197, v80, v81, v82
	v_max3_f32 v196, v196, v67, v68
	v_max3_f32 v197, v197, v83, v84
	v_max3_f32 v196, v196, v69, v70
	v_max3_f32 v197, v197, v85, v86
	s_waitcnt lgkmcnt(6)
	v_mfma_f32_32x32x16_bf16 v[0:15], v[148:151], v[226:229], v[0:15]
	ds_read_b64_tr_b16 v[156:157], v183 offset:12800
	ds_read_b64_tr_b16 v[158:159], v183 offset:13056
	v_max3_f32 v196, v196, v71, v72
	v_max3_f32 v197, v197, v87, v88
	v_max3_f32 v196, v196, v73, v74
	v_max3_f32 v197, v197, v89, v90
	v_max3_f32 v196, v196, v75, v76
	v_max3_f32 v197, v197, v91, v92
	s_waitcnt lgkmcnt(6)
	v_mfma_f32_32x32x16_bf16 v[48:63], v[128:131], v[136:139], v[48:63]
	ds_read_b64_tr_b16 v[214:215], v183 offset:1024
	ds_read_b64_tr_b16 v[216:217], v183 offset:1280
	v_max3_f32 v196, v196, v77, v78
	v_max3_f32 v197, v197, v93, v94
	v_max_f32_e32 v196, v196, v79
	v_max_f32_e32 v197, v197, v95
	v_max_f32_e32 v196, v196, v197
	v_mov_b32_e32 v197, v196
	s_waitcnt lgkmcnt(6)
	v_mfma_f32_32x32x16_bf16 v[48:63], v[132:135], v[140:143], v[48:63]
	ds_read_b64_tr_b16 v[218:219], v183 offset:5120
	ds_read_b64_tr_b16 v[220:221], v183 offset:5376
	v_permlane32_swap_b32_e32 v196, v197
	v_max_f32_e32 v196, v196, v197
	v_cmp_ge_f32_e32 vcc, s97, v196
	s_cmp_eq_u64 vcc, exec
	s_cselect_b64 s[42:43], -1, 0
	v_mov_b32_e32 v193, 1.0
	s_mov_b64 s[12:13], 0
	s_cmp_lg_u64 s[42:43], 0
	s_cbranch_scc1 .Lmla_ok_A
	v_max_f32_e32 v197, 0, v196
	v_exp_f32_e64 v193, -v197
	v_sub_f32_e32 v64, v64, v197
	v_sub_f32_e32 v65, v65, v197
	v_sub_f32_e32 v66, v66, v197
	v_sub_f32_e32 v67, v67, v197
	v_sub_f32_e32 v68, v68, v197
	v_sub_f32_e32 v69, v69, v197
	v_sub_f32_e32 v70, v70, v197
	v_sub_f32_e32 v71, v71, v197
	v_sub_f32_e32 v72, v72, v197
	v_sub_f32_e32 v73, v73, v197
	v_sub_f32_e32 v74, v74, v197
	v_sub_f32_e32 v75, v75, v197
	v_sub_f32_e32 v76, v76, v197
	v_sub_f32_e32 v77, v77, v197
	v_sub_f32_e32 v78, v78, v197
	v_sub_f32_e32 v79, v79, v197
	v_sub_f32_e32 v80, v80, v197
	v_sub_f32_e32 v81, v81, v197
	v_sub_f32_e32 v82, v82, v197
	v_sub_f32_e32 v83, v83, v197
	v_sub_f32_e32 v84, v84, v197
	v_sub_f32_e32 v85, v85, v197
	v_sub_f32_e32 v86, v86, v197
	v_sub_f32_e32 v87, v87, v197
	v_sub_f32_e32 v88, v88, v197
	v_sub_f32_e32 v89, v89, v197
	v_sub_f32_e32 v90, v90, v197
	v_sub_f32_e32 v91, v91, v197
	v_sub_f32_e32 v92, v92, v197
	v_sub_f32_e32 v93, v93, v197
	v_sub_f32_e32 v94, v94, v197
	v_sub_f32_e32 v95, v95, v197
	v_sub_f32_e32 v198, v198, v197
	v_sub_f32_e32 v199, v199, v197
	v_sub_f32_e32 v200, v200, v197
	v_sub_f32_e32 v201, v201, v197
	v_sub_f32_e32 v202, v202, v197
	v_sub_f32_e32 v203, v203, v197
	v_sub_f32_e32 v204, v204, v197
	v_sub_f32_e32 v205, v205, v197
	v_sub_f32_e32 v206, v206, v197
	v_sub_f32_e32 v207, v207, v197
	v_sub_f32_e32 v208, v208, v197
	v_sub_f32_e32 v209, v209, v197
	v_sub_f32_e32 v210, v210, v197
	v_sub_f32_e32 v211, v211, v197
	v_sub_f32_e32 v212, v212, v197
	v_sub_f32_e32 v213, v213, v197
	v_cmp_gt_f32_e64 s[12:13], 1.0, v193
.Lmla_ok_A:
	s_waitcnt lgkmcnt(6)
	v_mfma_f32_32x32x16_bf16 v[48:63], v[144:147], v[152:155], v[48:63]
	ds_read_b64_tr_b16 v[222:223], v183 offset:9216
	ds_read_b64_tr_b16 v[224:225], v183 offset:9472
	v_exp_f32_e32 v64, v64
	v_exp_f32_e32 v65, v65
	v_exp_f32_e32 v66, v66
	s_waitcnt lgkmcnt(6)
	v_mfma_f32_32x32x16_bf16 v[48:63], v[148:151], v[156:159], v[48:63]
	ds_read_b64_tr_b16 v[226:227], v183 offset:13312
	ds_read_b64_tr_b16 v[228:229], v183 offset:13568
	v_exp_f32_e32 v67, v67
	v_exp_f32_e32 v68, v68
	v_exp_f32_e32 v69, v69
	s_waitcnt lgkmcnt(6)
	v_mfma_f32_32x32x16_bf16 v[32:47], v[128:131], v[214:217], v[32:47]
	ds_read_b64_tr_b16 v[136:137], v183 offset:1536
	ds_read_b64_tr_b16 v[138:139], v183 offset:1792
	v_exp_f32_e32 v70, v70
	v_exp_f32_e32 v71, v71
	v_exp_f32_e32 v72, v72
	s_waitcnt lgkmcnt(6)
	v_mfma_f32_32x32x16_bf16 v[32:47], v[132:135], v[218:221], v[32:47]
	ds_read_b64_tr_b16 v[140:141], v183 offset:5632
	ds_read_b64_tr_b16 v[142:143], v183 offset:5888
	v_exp_f32_e32 v73, v73
	v_exp_f32_e32 v74, v74
	v_exp_f32_e32 v75, v75
	s_waitcnt lgkmcnt(6)
	v_mfma_f32_32x32x16_bf16 v[32:47], v[144:147], v[222:225], v[32:47]
	ds_read_b64_tr_b16 v[152:153], v183 offset:9728
	ds_read_b64_tr_b16 v[154:155], v183 offset:9984
	v_exp_f32_e32 v76, v76
	v_exp_f32_e32 v77, v77
	v_exp_f32_e32 v78, v78
	s_waitcnt lgkmcnt(6)
	v_mfma_f32_32x32x16_bf16 v[32:47], v[148:151], v[226:229], v[32:47]
	ds_read_b64_tr_b16 v[156:157], v183 offset:13824
	ds_read_b64_tr_b16 v[158:159], v183 offset:14080
	v_exp_f32_e32 v79, v79
	s_waitcnt lgkmcnt(6)
	v_mfma_f32_32x32x16_bf16 v[16:31], v[128:131], v[136:139], v[16:31]
	s_waitcnt lgkmcnt(4)
	v_mfma_f32_32x32x16_bf16 v[16:31], v[132:135], v[140:143], v[16:31]
	s_waitcnt lgkmcnt(2)
	v_mfma_f32_32x32x16_bf16 v[16:31], v[144:147], v[152:155], v[16:31]
	s_waitcnt lgkmcnt(0)
	v_mfma_f32_32x32x16_bf16 v[16:31], v[148:151], v[156:159], v[16:31]
	s_cmp_lg_u64 s[12:13], 0
	s_cbranch_scc0 .Lmla_nors_A
	s_and_saveexec_b64 s[20:21], s[40:41]
	ds_write_b32 v162, v193 offset:128
	s_or_b64 exec, exec, s[20:21]
	s_waitcnt lgkmcnt(0)
	v_add_u32_e32 v245, s37, v184
	ds_read_b128 v[214:217], v245 offset:128
	ds_read_b128 v[218:221], v245 offset:160
	ds_read_b128 v[222:225], v245 offset:192
	ds_read_b128 v[226:229], v245 offset:224
	s_waitcnt lgkmcnt(0)
	v_pk_mul_f32 v[0:1], v[0:1], v[214:215]
	v_pk_mul_f32 v[2:3], v[2:3], v[216:217]
	v_pk_mul_f32 v[4:5], v[4:5], v[218:219]
	v_pk_mul_f32 v[6:7], v[6:7], v[220:221]
	v_pk_mul_f32 v[8:9], v[8:9], v[222:223]
	v_pk_mul_f32 v[10:11], v[10:11], v[224:225]
	v_pk_mul_f32 v[12:13], v[12:13], v[226:227]
	v_pk_mul_f32 v[14:15], v[14:15], v[228:229]
	v_pk_mul_f32 v[48:49], v[48:49], v[214:215]
	v_pk_mul_f32 v[50:51], v[50:51], v[216:217]
	v_pk_mul_f32 v[52:53], v[52:53], v[218:219]
	v_pk_mul_f32 v[54:55], v[54:55], v[220:221]
	v_pk_mul_f32 v[56:57], v[56:57], v[222:223]
	v_pk_mul_f32 v[58:59], v[58:59], v[224:225]
	v_pk_mul_f32 v[60:61], v[60:61], v[226:227]
	v_pk_mul_f32 v[62:63], v[62:63], v[228:229]
	v_pk_mul_f32 v[32:33], v[32:33], v[214:215]
	v_pk_mul_f32 v[34:35], v[34:35], v[216:217]
	v_pk_mul_f32 v[36:37], v[36:37], v[218:219]
	v_pk_mul_f32 v[38:39], v[38:39], v[220:221]
	v_pk_mul_f32 v[40:41], v[40:41], v[222:223]
	v_pk_mul_f32 v[42:43], v[42:43], v[224:225]
	v_pk_mul_f32 v[44:45], v[44:45], v[226:227]
	v_pk_mul_f32 v[46:47], v[46:47], v[228:229]
	v_pk_mul_f32 v[16:17], v[16:17], v[214:215]
	v_pk_mul_f32 v[18:19], v[18:19], v[216:217]
	v_pk_mul_f32 v[20:21], v[20:21], v[218:219]
	v_pk_mul_f32 v[22:23], v[22:23], v[220:221]
	v_pk_mul_f32 v[24:25], v[24:25], v[222:223]
	v_pk_mul_f32 v[26:27], v[26:27], v[224:225]
	v_pk_mul_f32 v[28:29], v[28:29], v[226:227]
	v_pk_mul_f32 v[30:31], v[30:31], v[228:229]
.Lmla_nors_A:
	s_add_i32 s8, s52, 1
	s_cmp_lg_u32 s52, 2
	s_cselect_b32 s14, s8, 0
	s_add_i32 s8, s49, 1
	s_cmp_lg_u32 s49, 2
	s_cselect_b32 s15, s8, 0
	s_waitcnt vmcnt(2) lgkmcnt(0)
	s_barrier
	ds_read_b128 v[214:217], v166 offset:16384
	ds_read_b128 v[218:221], v166 offset:24576
	ds_read_b128 v[222:225], v167 offset:16384
	ds_read_b128 v[226:229], v167 offset:24576
	ds_read_b128 v[230:233], v168 offset:16384
	ds_read_b128 v[234:237], v168 offset:24576
	v_lshl_add_u32 v183, s14, 14, v192
	s_mov_b32 m0, s93
	s_lshl_b32 s8, s15, 14
	global_load_lds_dwordx4 v178, s[98:99]
	v_exp_f32_e32 v80, v80
	v_add_f32_e32 v243, v64, v65
	v_add_f32_e32 v244, v66, v67
	v_exp_f32_e32 v81, v81
	s_waitcnt lgkmcnt(4)
	v_mfma_f32_32x32x16_bf16 v[128:143], v[214:217], v[124:127], v[198:213]
	s_mov_b32 m0, s50
	s_add_i32 s12, s8, s44
	global_load_lds_dwordx4 v179, s[98:99]
	v_cvt_pk_bf16_f32 v64, v64, v65
	v_add_f32_e32 v243, v68, v243
	v_exp_f32_e32 v82, v82
	v_mfma_f32_32x32x16_bf16 v[144:159], v[218:221], v[124:127], v[198:213]
	ds_read_b128 v[214:217], v169 offset:16384
	ds_read_b128 v[218:221], v169 offset:24576
	v_cvt_pk_bf16_f32 v65, v66, v67
	v_add_f32_e32 v244, v69, v244
	v_exp_f32_e32 v83, v83
	s_waitcnt lgkmcnt(4)
	v_mfma_f32_32x32x16_bf16 v[128:143], v[222:225], v[120:123], v[128:143]
	s_mov_b32 m0, s51
	s_nop 0
	global_load_lds_dwordx4 v182, s[100:101]
	s_add_u32 s100, s100, 0x2000
	s_addc_u32 s101, s101, 0
	v_add_f32_e32 v243, v70, v243
	v_cvt_pk_bf16_f32 v66, v68, v69
	v_exp_f32_e32 v84, v84
	v_mfma_f32_32x32x16_bf16 v[144:159], v[226:229], v[120:123], v[144:159]
	ds_read_b128 v[222:225], v170 offset:16384
	ds_read_b128 v[226:229], v170 offset:24576
	v_add_f32_e32 v244, v71, v244
	v_exp_f32_e32 v85, v85
	v_add_f32_e32 v243, v72, v243
	s_waitcnt lgkmcnt(4)
	v_mfma_f32_32x32x16_bf16 v[128:143], v[230:233], v[116:119], v[128:143]
	s_mov_b32 m0, s12
	s_add_i32 s12, s8, s47
	global_load_lds_dwordx4 v180, s[98:99]
	v_cvt_pk_bf16_f32 v67, v70, v71
	v_exp_f32_e32 v86, v86
	v_add_f32_e32 v244, v73, v244
	v_mfma_f32_32x32x16_bf16 v[144:159], v[234:237], v[116:119], v[144:159]
	ds_read_b128 v[230:233], v171 offset:16384
	ds_read_b128 v[234:237], v171 offset:24576
	v_exp_f32_e32 v87, v87
	v_add_f32_e32 v243, v74, v243
	v_cvt_pk_bf16_f32 v68, v72, v73
	s_waitcnt lgkmcnt(4)
	v_mfma_f32_32x32x16_bf16 v[128:143], v[214:217], v[112:115], v[128:143]
	s_mov_b32 m0, s12
	s_nop 0
	global_load_lds_dwordx4 v181, s[98:99]
	s_add_u32 s98, s98, 0x40000
	s_addc_u32 s99, s99, 0
	v_exp_f32_e32 v88, v88
	v_add_f32_e32 v244, v75, v244
	v_exp_f32_e32 v89, v89
	v_mfma_f32_32x32x16_bf16 v[144:159], v[218:221], v[112:115], v[144:159]
	ds_read_b128 v[214:217], v172 offset:16384
	ds_read_b128 v[218:221], v172 offset:24576
	v_add_f32_e32 v243, v76, v243
	v_cvt_pk_bf16_f32 v69, v74, v75
	v_add_f32_e32 v244, v77, v244
	v_exp_f32_e32 v90, v90
	s_waitcnt lgkmcnt(4)
	v_mfma_f32_32x32x16_bf16 v[128:143], v[222:225], v[108:111], v[128:143]
	v_add_f32_e32 v243, v78, v243
	v_exp_f32_e32 v91, v91
	v_cvt_pk_bf16_f32 v70, v76, v77
	v_mfma_f32_32x32x16_bf16 v[144:159], v[226:229], v[108:111], v[144:159]
	ds_read_b128 v[222:225], v173 offset:16384
	ds_read_b128 v[226:229], v173 offset:24576
	v_add_f32_e32 v244, v79, v244
	v_exp_f32_e32 v92, v92
	v_add_f32_e32 v243, v80, v243
	s_waitcnt lgkmcnt(4)
	v_mfma_f32_32x32x16_bf16 v[128:143], v[230:233], v[104:107], v[128:143]
	v_cvt_pk_bf16_f32 v71, v78, v79
	v_exp_f32_e32 v93, v93
	v_add_f32_e32 v244, v81, v244
	v_mfma_f32_32x32x16_bf16 v[144:159], v[234:237], v[104:107], v[144:159]
	ds_read_b128 v[230:233], v174
	ds_read_b128 v[234:237], v174 offset:4096
	v_exp_f32_e32 v94, v94
	v_add_f32_e32 v243, v82, v243
	v_cvt_pk_bf16_f32 v80, v80, v81
	s_waitcnt lgkmcnt(4)
	v_mfma_f32_32x32x16_bf16 v[128:143], v[214:217], v[100:103], v[128:143]
	v_exp_f32_e32 v95, v95
	v_add_f32_e32 v244, v83, v244
	v_add_f32_e32 v243, v84, v243
	v_mfma_f32_32x32x16_bf16 v[144:159], v[218:221], v[100:103], v[144:159]
	ds_read_b128 v[214:217], v175
	ds_read_b128 v[218:221], v175 offset:4096
	v_cvt_pk_bf16_f32 v81, v82, v83
	v_add_f32_e32 v244, v85, v244
	v_add_f32_e32 v243, v86, v243
	v_cvt_pk_bf16_f32 v82, v84, v85
	s_waitcnt lgkmcnt(4)
	v_mfma_f32_32x32x16_bf16 v[128:143], v[222:225], v[96:99], v[128:143]
	v_add_f32_e32 v244, v87, v244
	v_add_f32_e32 v243, v88, v243
	v_cvt_pk_bf16_f32 v83, v86, v87
	v_add_f32_e32 v244, v89, v244
	v_mfma_f32_32x32x16_bf16 v[144:159], v[226:229], v[96:99], v[144:159]
	ds_read_b128 v[222:225], v176
	ds_read_b128 v[226:229], v176 offset:4096
	v_add_f32_e32 v243, v90, v243
	v_cvt_pk_bf16_f32 v84, v88, v89
	v_add_f32_e32 v244, v91, v244
	v_add_f32_e32 v243, v92, v243
	s_waitcnt lgkmcnt(4)
	v_mfma_f32_32x32x16_bf16 v[128:143], v[230:233], v[246:249], v[128:143]
	v_cvt_pk_bf16_f32 v85, v90, v91
	v_add_f32_e32 v244, v93, v244
	v_add_f32_e32 v243, v94, v243
	v_cvt_pk_bf16_f32 v86, v92, v93
	v_mfma_f32_32x32x16_bf16 v[144:159], v[234:237], v[246:249], v[144:159]
	ds_read_b128 v[230:233], v177
	ds_read_b128 v[234:237], v177 offset:4096
	v_add_f32_e32 v244, v95, v244
	v_cvt_pk_bf16_f32 v87, v94, v95
	v_add_f32_e32 v243, v243, v244
	v_mov_b32_e32 v244, v243
	s_waitcnt lgkmcnt(4)
	v_mfma_f32_32x32x16_bf16 v[128:143], v[214:217], v[250:253], v[128:143]
	v_permlane32_swap_b32_e32 v243, v244
	v_add_f32_e32 v243, v243, v244
	v_fma_f32 v163, v163, v193, v243
	v_mfma_f32_32x32x16_bf16 v[144:159], v[218:221], v[250:253], v[144:159]
	ds_read_b64_tr_b16 v[214:215], v183
	ds_read_b64_tr_b16 v[216:217], v183 offset:256
	ds_read_b64_tr_b16 v[218:219], v183 offset:4096
	ds_read_b64_tr_b16 v[220:221], v183 offset:4352
	s_waitcnt lgkmcnt(6)
	v_mfma_f32_32x32x16_bf16 v[128:143], v[222:225], v[186:189], v[128:143]
	v_mfma_f32_32x32x16_bf16 v[144:159], v[226:229], v[186:189], v[144:159]
	ds_read_b64_tr_b16 v[222:223], v183 offset:8192
	ds_read_b64_tr_b16 v[224:225], v183 offset:8448
	ds_read_b64_tr_b16 v[226:227], v183 offset:12288
	ds_read_b64_tr_b16 v[228:229], v183 offset:12544
	s_waitcnt lgkmcnt(8)
	v_mfma_f32_32x32x16_bf16 v[128:143], v[230:233], v[238:241], v[128:143]
	v_mfma_f32_32x32x16_bf16 v[144:159], v[234:237], v[238:241], v[144:159]
	s_waitcnt lgkmcnt(6)
	v_mfma_f32_32x32x16_bf16 v[0:15], v[64:67], v[214:217], v[0:15]
	ds_read_b64_tr_b16 v[72:73], v183 offset:512
	ds_read_b64_tr_b16 v[74:75], v183 offset:768
	s_waitcnt lgkmcnt(6)
	v_mfma_f32_32x32x16_bf16 v[0:15], v[68:71], v[218:221], v[0:15]
	ds_read_b64_tr_b16 v[76:77], v183 offset:4608
	ds_read_b64_tr_b16 v[78:79], v183 offset:4864
	s_waitcnt lgkmcnt(6)
	v_mfma_f32_32x32x16_bf16 v[0:15], v[80:83], v[222:225], v[0:15]
	ds_read_b64_tr_b16 v[88:89], v183 offset:8704
	ds_read_b64_tr_b16 v[90:91], v183 offset:8960
	v_max3_f32 v196, v128, v129, v130
	v_max3_f32 v197, v144, v145, v146
	v_max3_f32 v196, v196, v131, v132
	v_max3_f32 v197, v197, v147, v148
	v_max3_f32 v196, v196, v133, v134
	v_max3_f32 v197, v197, v149, v150
	s_waitcnt lgkmcnt(6)
	v_mfma_f32_32x32x16_bf16 v[0:15], v[84:87], v[226:229], v[0:15]
	ds_read_b64_tr_b16 v[92:93], v183 offset:12800
	ds_read_b64_tr_b16 v[94:95], v183 offset:13056
	v_max3_f32 v196, v196, v135, v136
	v_max3_f32 v197, v197, v151, v152
	v_max3_f32 v196, v196, v137, v138
	v_max3_f32 v197, v197, v153, v154
	v_max3_f32 v196, v196, v139, v140
	v_max3_f32 v197, v197, v155, v156
	s_waitcnt lgkmcnt(6)
	v_mfma_f32_32x32x16_bf16 v[48:63], v[64:67], v[72:75], v[48:63]
	ds_read_b64_tr_b16 v[214:215], v183 offset:1024
	ds_read_b64_tr_b16 v[216:217], v183 offset:1280
	v_max3_f32 v196, v196, v141, v142
	v_max3_f32 v197, v197, v157, v158
	v_max_f32_e32 v196, v196, v143
	v_max_f32_e32 v197, v197, v159
	v_max_f32_e32 v196, v196, v197
	v_mov_b32_e32 v197, v196
	s_waitcnt lgkmcnt(6)
	v_mfma_f32_32x32x16_bf16 v[48:63], v[68:71], v[76:79], v[48:63]
	ds_read_b64_tr_b16 v[218:219], v183 offset:5120
	ds_read_b64_tr_b16 v[220:221], v183 offset:5376
	v_permlane32_swap_b32_e32 v196, v197
	v_max_f32_e32 v196, v196, v197
	v_cmp_ge_f32_e32 vcc, s97, v196
	s_cmp_eq_u64 vcc, exec
	s_cselect_b64 s[42:43], -1, 0
	v_mov_b32_e32 v242, 1.0
	s_mov_b64 s[12:13], 0
	s_cmp_lg_u64 s[42:43], 0
	s_cbranch_scc1 .Lmla_ok_B
	v_max_f32_e32 v197, 0, v196
	v_exp_f32_e64 v242, -v197
	v_sub_f32_e32 v128, v128, v197
	v_sub_f32_e32 v129, v129, v197
	v_sub_f32_e32 v130, v130, v197
	v_sub_f32_e32 v131, v131, v197
	v_sub_f32_e32 v132, v132, v197
	v_sub_f32_e32 v133, v133, v197
	v_sub_f32_e32 v134, v134, v197
	v_sub_f32_e32 v135, v135, v197
	v_sub_f32_e32 v136, v136, v197
	v_sub_f32_e32 v137, v137, v197
	v_sub_f32_e32 v138, v138, v197
	v_sub_f32_e32 v139, v139, v197
	v_sub_f32_e32 v140, v140, v197
	v_sub_f32_e32 v141, v141, v197
	v_sub_f32_e32 v142, v142, v197
	v_sub_f32_e32 v143, v143, v197
	v_sub_f32_e32 v144, v144, v197
	v_sub_f32_e32 v145, v145, v197
	v_sub_f32_e32 v146, v146, v197
	v_sub_f32_e32 v147, v147, v197
	v_sub_f32_e32 v148, v148, v197
	v_sub_f32_e32 v149, v149, v197
	v_sub_f32_e32 v150, v150, v197
	v_sub_f32_e32 v151, v151, v197
	v_sub_f32_e32 v152, v152, v197
	v_sub_f32_e32 v153, v153, v197
	v_sub_f32_e32 v154, v154, v197
	v_sub_f32_e32 v155, v155, v197
	v_sub_f32_e32 v156, v156, v197
	v_sub_f32_e32 v157, v157, v197
	v_sub_f32_e32 v158, v158, v197
	v_sub_f32_e32 v159, v159, v197
	v_sub_f32_e32 v198, v198, v197
	v_sub_f32_e32 v199, v199, v197
	v_sub_f32_e32 v200, v200, v197
	v_sub_f32_e32 v201, v201, v197
	v_sub_f32_e32 v202, v202, v197
	v_sub_f32_e32 v203, v203, v197
	v_sub_f32_e32 v204, v204, v197
	v_sub_f32_e32 v205, v205, v197
	v_sub_f32_e32 v206, v206, v197
	v_sub_f32_e32 v207, v207, v197
	v_sub_f32_e32 v208, v208, v197
	v_sub_f32_e32 v209, v209, v197
	v_sub_f32_e32 v210, v210, v197
	v_sub_f32_e32 v211, v211, v197
	v_sub_f32_e32 v212, v212, v197
	v_sub_f32_e32 v213, v213, v197
	v_cmp_gt_f32_e64 s[12:13], 1.0, v242
.Lmla_ok_B:
	s_waitcnt lgkmcnt(6)
	v_mfma_f32_32x32x16_bf16 v[48:63], v[80:83], v[88:91], v[48:63]
	ds_read_b64_tr_b16 v[222:223], v183 offset:9216
	ds_read_b64_tr_b16 v[224:225], v183 offset:9472
	v_exp_f32_e32 v128, v128
	v_exp_f32_e32 v129, v129
	v_exp_f32_e32 v130, v130
	s_waitcnt lgkmcnt(6)
	v_mfma_f32_32x32x16_bf16 v[48:63], v[84:87], v[92:95], v[48:63]
	ds_read_b64_tr_b16 v[226:227], v183 offset:13312
	ds_read_b64_tr_b16 v[228:229], v183 offset:13568
	v_exp_f32_e32 v131, v131
	v_exp_f32_e32 v132, v132
	v_exp_f32_e32 v133, v133
	s_waitcnt lgkmcnt(6)
	v_mfma_f32_32x32x16_bf16 v[32:47], v[64:67], v[214:217], v[32:47]
	ds_read_b64_tr_b16 v[72:73], v183 offset:1536
	ds_read_b64_tr_b16 v[74:75], v183 offset:1792
	v_exp_f32_e32 v134, v134
	v_exp_f32_e32 v135, v135
	v_exp_f32_e32 v136, v136
	s_waitcnt lgkmcnt(6)
	v_mfma_f32_32x32x16_bf16 v[32:47], v[68:71], v[218:221], v[32:47]
	ds_read_b64_tr_b16 v[76:77], v183 offset:5632
	ds_read_b64_tr_b16 v[78:79], v183 offset:5888
	v_exp_f32_e32 v137, v137
	v_exp_f32_e32 v138, v138
	v_exp_f32_e32 v139, v139
	s_waitcnt lgkmcnt(6)
	v_mfma_f32_32x32x16_bf16 v[32:47], v[80:83], v[222:225], v[32:47]
	ds_read_b64_tr_b16 v[88:89], v183 offset:9728
	ds_read_b64_tr_b16 v[90:91], v183 offset:9984
	v_exp_f32_e32 v140, v140
	v_exp_f32_e32 v141, v141
	v_exp_f32_e32 v142, v142
	s_waitcnt lgkmcnt(6)
	v_mfma_f32_32x32x16_bf16 v[32:47], v[84:87], v[226:229], v[32:47]
	ds_read_b64_tr_b16 v[92:93], v183 offset:13824
	ds_read_b64_tr_b16 v[94:95], v183 offset:14080
	v_exp_f32_e32 v143, v143
	s_waitcnt lgkmcnt(6)
	v_mfma_f32_32x32x16_bf16 v[16:31], v[64:67], v[72:75], v[16:31]
	s_waitcnt lgkmcnt(4)
	v_mfma_f32_32x32x16_bf16 v[16:31], v[68:71], v[76:79], v[16:31]
	s_waitcnt lgkmcnt(2)
	v_mfma_f32_32x32x16_bf16 v[16:31], v[80:83], v[88:91], v[16:31]
	s_waitcnt lgkmcnt(0)
	v_mfma_f32_32x32x16_bf16 v[16:31], v[84:87], v[92:95], v[16:31]
	s_cmp_lg_u64 s[12:13], 0
	s_cbranch_scc0 .Lmla_nors_B
	s_and_saveexec_b64 s[20:21], s[40:41]
	ds_write_b32 v162, v242 offset:128
	s_or_b64 exec, exec, s[20:21]
	s_waitcnt lgkmcnt(0)
	v_add_u32_e32 v245, s37, v184
	ds_read_b128 v[214:217], v245 offset:128
	ds_read_b128 v[218:221], v245 offset:160
	ds_read_b128 v[222:225], v245 offset:192
	ds_read_b128 v[226:229], v245 offset:224
	s_waitcnt lgkmcnt(0)
	v_pk_mul_f32 v[0:1], v[0:1], v[214:215]
	v_pk_mul_f32 v[2:3], v[2:3], v[216:217]
	v_pk_mul_f32 v[4:5], v[4:5], v[218:219]
	v_pk_mul_f32 v[6:7], v[6:7], v[220:221]
	v_pk_mul_f32 v[8:9], v[8:9], v[222:223]
	v_pk_mul_f32 v[10:11], v[10:11], v[224:225]
	v_pk_mul_f32 v[12:13], v[12:13], v[226:227]
	v_pk_mul_f32 v[14:15], v[14:15], v[228:229]
	v_pk_mul_f32 v[48:49], v[48:49], v[214:215]
	v_pk_mul_f32 v[50:51], v[50:51], v[216:217]
	v_pk_mul_f32 v[52:53], v[52:53], v[218:219]
	v_pk_mul_f32 v[54:55], v[54:55], v[220:221]
	v_pk_mul_f32 v[56:57], v[56:57], v[222:223]
	v_pk_mul_f32 v[58:59], v[58:59], v[224:225]
	v_pk_mul_f32 v[60:61], v[60:61], v[226:227]
	v_pk_mul_f32 v[62:63], v[62:63], v[228:229]
	v_pk_mul_f32 v[32:33], v[32:33], v[214:215]
	v_pk_mul_f32 v[34:35], v[34:35], v[216:217]
	v_pk_mul_f32 v[36:37], v[36:37], v[218:219]
	v_pk_mul_f32 v[38:39], v[38:39], v[220:221]
	v_pk_mul_f32 v[40:41], v[40:41], v[222:223]
	v_pk_mul_f32 v[42:43], v[42:43], v[224:225]
	v_pk_mul_f32 v[44:45], v[44:45], v[226:227]
	v_pk_mul_f32 v[46:47], v[46:47], v[228:229]
	v_pk_mul_f32 v[16:17], v[16:17], v[214:215]
	v_pk_mul_f32 v[18:19], v[18:19], v[216:217]
	v_pk_mul_f32 v[20:21], v[20:21], v[218:219]
	v_pk_mul_f32 v[22:23], v[22:23], v[220:221]
	v_pk_mul_f32 v[24:25], v[24:25], v[222:223]
	v_pk_mul_f32 v[26:27], v[26:27], v[224:225]
	v_pk_mul_f32 v[28:29], v[28:29], v[226:227]
	v_pk_mul_f32 v[30:31], v[30:31], v[228:229]
.Lmla_nors_B:
	s_add_i32 s8, s14, 1
	s_cmp_lg_u32 s14, 2
	s_cselect_b32 s52, s8, 0
	s_add_i32 s8, s15, 1
	s_cmp_lg_u32 s15, 2
	s_cselect_b32 s49, s8, 0
	s_waitcnt vmcnt(2) lgkmcnt(0)
	s_barrier
	s_add_i32 s48, s48, 2
	s_cmp_lt_u32 s48, 61
	s_cbranch_scc1 .Lmla_loop
	v_mov_b32_e32 v236, v128
	v_mov_b32_e32 v238, v129
	v_mov_b32_e32 v234, v130
	v_mov_b32_e32 v237, v131
	v_mov_b32_e32 v233, v132
	v_mov_b32_e32 v235, v133
	v_mov_b32_e32 v231, v134
	v_mov_b32_e32 v232, v135
	v_mov_b32_e32 v228, v136
	v_mov_b32_e32 v230, v137
	v_mov_b32_e32 v227, v138
	v_mov_b32_e32 v229, v139
	v_mov_b32_e32 v224, v140
	v_mov_b32_e32 v226, v141
	v_mov_b32_e32 v223, v142
	v_mov_b32_e32 v225, v143
	v_mov_b32_e32 v134, v152
	v_mov_b32_e32 v135, v153
	v_mov_b32_e32 v132, v154
	v_mov_b32_e32 v133, v155
	v_mov_b32_e32 v130, v156
	v_mov_b32_e32 v131, v157
	v_mov_b32_e32 v128, v158
	v_mov_b32_e32 v129, v159
	v_mov_b32_e32 v158, v144
	v_mov_b32_e32 v159, v145
	v_mov_b32_e32 v156, v146
	v_mov_b32_e32 v157, v147
	v_mov_b32_e32 v154, v148
	v_mov_b32_e32 v155, v149
	v_mov_b32_e32 v152, v150
	v_mov_b32_e32 v153, v151
	s_waitcnt vmcnt(0)
	s_barrier
	v_sub_f32_e32 v222, 0, v198
	v_mov_b32_e32 v144, v242
	v_mov_b32_e32 v198, v242
	v_add_u32_e32 v199, 0x8000, v166
	v_add_u32_e32 v200, 0x8000, v167
	v_add_u32_e32 v201, 0x8000, v168
	v_add_u32_e32 v202, 0x8000, v169
	v_add_u32_e32 v214, 0x8000, v170
	v_add_u32_e32 v215, 0x8000, v171
	v_add_u32_e32 v216, 0x8000, v172
	v_add_u32_e32 v217, 0x8000, v173
	v_add_u32_e32 v219, 0x2000, v174
	v_add_u32_e32 v218, 0x2000, v175
	v_add_u32_e32 v220, 0x2000, v176
	v_add_u32_e32 v221, 0x2000, v177
	v_mov_b32_e32 v203, v191
	v_mov_b32_e32 v204, 0x358637bd
	v_mov_b32_e32 v205, 0x260
	v_mov_b32_e32 v206, 1
	v_mov_b32_e32 v207, 0xf149f2ca
	v_mbcnt_lo_u32_b32 v208, -1, 0
	v_mbcnt_hi_u32_b32 v208, -1, v208
	v_mov_b32_e32 v209, 0x1450
	v_mov_b64_e32 v[210:211], 0x400
	v_mov_b32_e32 v212, 0x1c70
	v_and_b32_e32 v213, 63, v191
	v_mov_b32_e32 v242, 0
	v_mov_b32_e32 v243, 0
	v_mov_b32_e32 v244, 0
	v_mov_b32_e32 v245, 0
